# short-K (K=256) q-latent GEMM loop left in its original two-stage form; pipelined loop only for K>=1024 GEMMs
# speedup vs baseline: 1.0004x; 1.0004x over previous
;   __device__ __forceinline__ u16* wqx(int l) const { return (u16*)(ws + l * LAYER_W + O_WQX); }
;   __device__ __forceinline__ u16* P() const { return (u16*)(ws + O_P); }
; DI f32x4 mfma16(bf16x8 a, bf16x8 b, f32x4 c) { return __builtin_amdgcn_mfma_f32_16x16x32_bf16(a, b, c, 0, 0, 0); }
; #define GLOAD(kt) { GL1(0, kt) GL1(1, kt) GL1(2, kt) GL1(3, kt) }
; #define SSTORE(buf)                              \
;   {                                              \
;     char* as_ = smem + (buf) * BUF;              \
;     char* bs_ = as_ + ASZ;                       \
;     SS1(0) SS1(1) SS1(2) SS1(3)                  \
;   }
; template <int MT, int NT>
; DI void gemm_core(const u16* __restrict__ A, int lda, const u16* __restrict__ B, int ldb, int K,
;                   f32x4 (&acc)[MT][NT], char* smem) {
;     ...
;   for (int kt = 0; kt < nk; ++kt) {
;     __syncthreads();
;     SSTORE((kt + 1) & 1);
;     { const int kn_ = (kt + 2 < nk) ? kt + 2 : nk - 1; GLOAD(kn_); }
;     const char* as = smem + (kt & 1) * BUF;
;     const char* bs = as + ASZ;
; #pragma unroll
;     for (int kk = 0; kk < 2; ++kk) {
;       bf16x8 xf[MT], wf[NT];
; #pragma unroll
;       for (int mi = 0; mi < MT; ++mi)
;         xf[mi] = *(const bf16x8*)(as + (wm * (MT * 16) + mi * 16 + fr) * 128 + (((kk * 4 + fq) ^ fsw) * 16));
; #pragma unroll
;       for (int ni = 0; ni < NT; ++ni)
;         wf[ni] = *(const bf16x8*)(bs + (wn * (NT * 16) + ni * 16 + fr) * 128 + (((kk * 4 + fq) ^ fsw) * 16));
;       __builtin_amdgcn_s_setprio(1);
; #pragma unroll
;       for (int mi = 0; mi < MT; ++mi)
; #pragma unroll
;         for (int ni = 0; ni < NT; ++ni) acc[mi][ni] = mfma16(wf[ni], xf[mi], acc[mi][ni]);
;       __builtin_amdgcn_s_setprio(0);
;     }
;   }
; DI void qx_tile(const Params& p, int l, int rt, int ct, char* smem) {
;     ...
;   gemm_core<4, 8>(p.P() + (size_t)r0 * PC + CQ, PC, p.wqx(l) + (size_t)c0 * KP256, KP256, 256, acc, smem);
.LBB0_235:
	s_add_i32 s6, s1, 0x10000
	s_and_b32 s7, s6, 0x10000
	s_cmp_eq_u32 s1, 0
	v_add3_u32 v190, s7, v0, v173
	s_cselect_b32 s54, 0x100, s63
	s_waitcnt lgkmcnt(0)
	s_barrier
	v_add3_u32 v191, s7, v175, v173
	v_add3_u32 v192, s7, v184, v173
	v_add3_u32 v193, s7, v185, v173
	s_waitcnt vmcnt(4)
	ds_write_b128 v190, v[110:113]
	s_waitcnt vmcnt(0)
	ds_write_b128 v190, v[126:129] offset:32768
	ds_write_b128 v191, v[106:109]
	ds_write_b128 v191, v[122:125] offset:32768
	ds_write_b128 v192, v[102:105]
	ds_write_b128 v192, v[118:121] offset:32768
	ds_write_b128 v193, v[98:101]
	ds_write_b128 v193, v[114:117] offset:32768
	v_lshl_add_u64 v[98:99], v[162:163], 0, s[54:55]
	v_lshl_add_u64 v[100:101], v[164:165], 0, s[54:55]
	v_lshl_add_u64 v[102:103], v[166:167], 0, s[54:55]
	v_lshl_add_u64 v[104:105], v[168:169], 0, s[54:55]
	v_lshl_add_u64 v[114:115], v[176:177], 0, s[54:55]
	v_lshl_add_u64 v[116:117], v[178:179], 0, s[54:55]
	v_lshl_add_u64 v[190:191], v[180:181], 0, s[54:55]
	v_lshl_add_u64 v[192:193], v[182:183], 0, s[54:55]
	global_load_dwordx4 v[110:113], v[98:99], off
	global_load_dwordx4 v[126:129], v[100:101], off
	global_load_dwordx4 v[106:109], v[102:103], off
	global_load_dwordx4 v[122:125], v[104:105], off
	s_nop 0
	global_load_dwordx4 v[102:105], v[114:115], off
	global_load_dwordx4 v[118:121], v[116:117], off
	global_load_dwordx4 v[98:101], v[190:191], off
	s_nop 0
	global_load_dwordx4 v[114:117], v[192:193], off
	s_and_b32 s1, s1, 0x10000
	v_or_b32_e32 v190, s1, v186
	v_add_u32_e32 v216, v190, v187
	v_add_u32_e32 v248, v190, v188
	ds_read_b128 v[190:193], v216
	ds_read_b128 v[208:211], v216 offset:2048
	ds_read_b128 v[212:215], v216 offset:4096
	ds_read_b128 v[216:219], v216 offset:6144
	ds_read_b128 v[220:223], v248 offset:32768
	ds_read_b128 v[224:227], v248 offset:34816
	ds_read_b128 v[228:231], v248 offset:36864
	ds_read_b128 v[232:235], v248 offset:38912
	ds_read_b128 v[236:239], v248 offset:40960
	ds_read_b128 v[240:243], v248 offset:43008
	ds_read_b128 v[244:247], v248 offset:45056
	ds_read_b128 v[248:251], v248 offset:47104
	s_setprio 1
	s_waitcnt lgkmcnt(7)
	v_mfma_f32_16x16x32_bf16 v[158:161], v[220:223], v[190:193], v[158:161]
	s_waitcnt lgkmcnt(6)
	v_mfma_f32_16x16x32_bf16 v[154:157], v[224:227], v[190:193], v[154:157]
	s_waitcnt lgkmcnt(5)
	v_mfma_f32_16x16x32_bf16 v[150:153], v[228:231], v[190:193], v[150:153]
	s_waitcnt lgkmcnt(4)
	v_mfma_f32_16x16x32_bf16 v[146:149], v[232:235], v[190:193], v[146:149]
	s_waitcnt lgkmcnt(3)
	v_mfma_f32_16x16x32_bf16 v[142:145], v[236:239], v[190:193], v[142:145]
	s_waitcnt lgkmcnt(2)
	v_mfma_f32_16x16x32_bf16 v[138:141], v[240:243], v[190:193], v[138:141]
	s_waitcnt lgkmcnt(1)
	v_mfma_f32_16x16x32_bf16 v[134:137], v[244:247], v[190:193], v[134:137]
	s_waitcnt lgkmcnt(0)
	v_mfma_f32_16x16x32_bf16 v[130:133], v[248:251], v[190:193], v[130:133]
	v_mfma_f32_16x16x32_bf16 v[94:97], v[220:223], v[208:211], v[94:97]
	v_mfma_f32_16x16x32_bf16 v[90:93], v[224:227], v[208:211], v[90:93]
	v_mfma_f32_16x16x32_bf16 v[86:89], v[228:231], v[208:211], v[86:89]
	v_mfma_f32_16x16x32_bf16 v[82:85], v[232:235], v[208:211], v[82:85]
	v_mfma_f32_16x16x32_bf16 v[78:81], v[236:239], v[208:211], v[78:81]
	v_mfma_f32_16x16x32_bf16 v[74:77], v[240:243], v[208:211], v[74:77]
	v_mfma_f32_16x16x32_bf16 v[70:73], v[244:247], v[208:211], v[70:73]
	v_mfma_f32_16x16x32_bf16 v[66:69], v[248:251], v[208:211], v[66:69]
	v_mfma_f32_16x16x32_bf16 v[62:65], v[220:223], v[212:215], v[62:65]
	v_mfma_f32_16x16x32_bf16 v[58:61], v[224:227], v[212:215], v[58:61]
	v_mfma_f32_16x16x32_bf16 v[54:57], v[228:231], v[212:215], v[54:57]
	v_mfma_f32_16x16x32_bf16 v[50:53], v[232:235], v[212:215], v[50:53]
	v_mfma_f32_16x16x32_bf16 v[46:49], v[236:239], v[212:215], v[46:49]
	v_mfma_f32_16x16x32_bf16 v[42:45], v[240:243], v[212:215], v[42:45]
	v_mfma_f32_16x16x32_bf16 v[38:41], v[244:247], v[212:215], v[38:41]
	v_mfma_f32_16x16x32_bf16 v[34:37], v[248:251], v[212:215], v[34:37]
	v_mfma_f32_16x16x32_bf16 v[30:33], v[220:223], v[216:219], v[30:33]
	v_mfma_f32_16x16x32_bf16 v[26:29], v[224:227], v[216:219], v[26:29]
	v_mfma_f32_16x16x32_bf16 v[22:25], v[228:231], v[216:219], v[22:25]
	v_mfma_f32_16x16x32_bf16 v[18:21], v[232:235], v[216:219], v[18:21]
	v_mfma_f32_16x16x32_bf16 v[14:17], v[236:239], v[216:219], v[14:17]
	v_mfma_f32_16x16x32_bf16 v[10:13], v[240:243], v[216:219], v[10:13]
	v_mfma_f32_16x16x32_bf16 v[6:9], v[244:247], v[216:219], v[6:9]
	v_mfma_f32_16x16x32_bf16 v[2:5], v[248:251], v[216:219], v[2:5]
	s_setprio 0
	v_or_b32_e32 v220, s1, v189
	v_add_u32_e32 v216, v220, v187
	v_add_u32_e32 v248, v220, v188
	ds_read_b128 v[190:193], v216
	ds_read_b128 v[208:211], v216 offset:2048
	ds_read_b128 v[212:215], v216 offset:4096
	ds_read_b128 v[216:219], v216 offset:6144
	ds_read_b128 v[220:223], v248 offset:32768
	ds_read_b128 v[224:227], v248 offset:34816
	ds_read_b128 v[228:231], v248 offset:36864
	ds_read_b128 v[232:235], v248 offset:38912
	ds_read_b128 v[236:239], v248 offset:40960
	ds_read_b128 v[240:243], v248 offset:43008
	ds_read_b128 v[244:247], v248 offset:45056
	ds_read_b128 v[248:251], v248 offset:47104
	s_setprio 1
	s_waitcnt lgkmcnt(7)
	v_mfma_f32_16x16x32_bf16 v[158:161], v[220:223], v[190:193], v[158:161]
	s_waitcnt lgkmcnt(6)
	v_mfma_f32_16x16x32_bf16 v[154:157], v[224:227], v[190:193], v[154:157]
	s_waitcnt lgkmcnt(5)
	v_mfma_f32_16x16x32_bf16 v[150:153], v[228:231], v[190:193], v[150:153]
	s_waitcnt lgkmcnt(4)
	v_mfma_f32_16x16x32_bf16 v[146:149], v[232:235], v[190:193], v[146:149]
	s_waitcnt lgkmcnt(3)
	v_mfma_f32_16x16x32_bf16 v[142:145], v[236:239], v[190:193], v[142:145]
	s_waitcnt lgkmcnt(2)
; DI f32x4 mfma16(bf16x8 a, bf16x8 b, f32x4 c) { return __builtin_amdgcn_mfma_f32_16x16x32_bf16(a, b, c, 0, 0, 0); }
; #define GLOAD(kt) { GL1(0, kt) GL1(1, kt) GL1(2, kt) GL1(3, kt) }
; #define SSTORE(buf)                              \
;   {                                              \
;     char* as_ = smem + (buf) * BUF;              \
;     char* bs_ = as_ + ASZ;                       \
;     SS1(0) SS1(1) SS1(2) SS1(3)                  \
;   }
; #define EPI_LOOP(MT_, NT_)                                                \
;   const int l_ = ltid() & 63, w_ = ltid() >> 6;                           \
;   const int wm_ = w_ >> 1, wn_ = w_ & 1, fr_ = l_ & 15, fq_ = l_ >> 4;    \
;   _Pragma("unroll") for (int mi = 0; mi < MT_; ++mi)                      \
;   _Pragma("unroll") for (int ni = 0; ni < NT_; ++ni)
; template <int MT, int NT>
; DI void gemm_core(const u16* __restrict__ A, int lda, const u16* __restrict__ B, int ldb, int K,
;                   f32x4 (&acc)[MT][NT], char* smem) {
;     ...
;   for (int kt = 0; kt < nk; ++kt) {
;     __syncthreads();
;     SSTORE((kt + 1) & 1);
;     { const int kn_ = (kt + 2 < nk) ? kt + 2 : nk - 1; GLOAD(kn_); }
;     const char* as = smem + (kt & 1) * BUF;
;     const char* bs = as + ASZ;
; #pragma unroll
;     for (int kk = 0; kk < 2; ++kk) {
;       bf16x8 xf[MT], wf[NT];
; #pragma unroll
;       for (int mi = 0; mi < MT; ++mi)
;         xf[mi] = *(const bf16x8*)(as + (wm * (MT * 16) + mi * 16 + fr) * 128 + (((kk * 4 + fq) ^ fsw) * 16));
; #pragma unroll
;       for (int ni = 0; ni < NT; ++ni)
;         wf[ni] = *(const bf16x8*)(bs + (wn * (NT * 16) + ni * 16 + fr) * 128 + (((kk * 4 + fq) ^ fsw) * 16));
;       __builtin_amdgcn_s_setprio(1);
; #pragma unroll
;       for (int mi = 0; mi < MT; ++mi)
; #pragma unroll
;         for (int ni = 0; ni < NT; ++ni) acc[mi][ni] = mfma16(wf[ni], xf[mi], acc[mi][ni]);
;       __builtin_amdgcn_s_setprio(0);
;     }
;   }
; DI void qx_tile(const Params& p, int l, int rt, int ct, char* smem) {
;     ...
;   EPI_LOOP(4, 8) {
;     const int rl = wm_ * 64 + mi * 16 + fr_, col = c0 + wn_ * 128 + ni * 16 + fq_ * 4;
;     const float rs = rsv[rl];
;     uint2 o;
;     o.x = pack2(acc[mi][ni][0] * rs, acc[mi][ni][1] * rs); o.y = pack2(acc[mi][ni][2] * rs, acc[mi][ni][3] * rs);
;     *(uint2*)(QX + (size_t)(r0 + rl) * LDQ + col) = o;
;   }
	v_mfma_f32_16x16x32_bf16 v[138:141], v[240:243], v[190:193], v[138:141]
	s_waitcnt lgkmcnt(1)
	v_mfma_f32_16x16x32_bf16 v[134:137], v[244:247], v[190:193], v[134:137]
	s_waitcnt lgkmcnt(0)
	v_mfma_f32_16x16x32_bf16 v[130:133], v[248:251], v[190:193], v[130:133]
	v_mfma_f32_16x16x32_bf16 v[94:97], v[220:223], v[208:211], v[94:97]
	v_mfma_f32_16x16x32_bf16 v[90:93], v[224:227], v[208:211], v[90:93]
	v_mfma_f32_16x16x32_bf16 v[86:89], v[228:231], v[208:211], v[86:89]
	v_mfma_f32_16x16x32_bf16 v[82:85], v[232:235], v[208:211], v[82:85]
	v_mfma_f32_16x16x32_bf16 v[78:81], v[236:239], v[208:211], v[78:81]
	v_mfma_f32_16x16x32_bf16 v[74:77], v[240:243], v[208:211], v[74:77]
	v_mfma_f32_16x16x32_bf16 v[70:73], v[244:247], v[208:211], v[70:73]
	v_mfma_f32_16x16x32_bf16 v[66:69], v[248:251], v[208:211], v[66:69]
	v_mfma_f32_16x16x32_bf16 v[62:65], v[220:223], v[212:215], v[62:65]
	v_mfma_f32_16x16x32_bf16 v[58:61], v[224:227], v[212:215], v[58:61]
	v_mfma_f32_16x16x32_bf16 v[54:57], v[228:231], v[212:215], v[54:57]
	v_mfma_f32_16x16x32_bf16 v[50:53], v[232:235], v[212:215], v[50:53]
	v_mfma_f32_16x16x32_bf16 v[46:49], v[236:239], v[212:215], v[46:49]
	v_mfma_f32_16x16x32_bf16 v[42:45], v[240:243], v[212:215], v[42:45]
	v_mfma_f32_16x16x32_bf16 v[38:41], v[244:247], v[212:215], v[38:41]
	v_mfma_f32_16x16x32_bf16 v[34:37], v[248:251], v[212:215], v[34:37]
	v_mfma_f32_16x16x32_bf16 v[30:33], v[220:223], v[216:219], v[30:33]
	v_mfma_f32_16x16x32_bf16 v[26:29], v[224:227], v[216:219], v[26:29]
	v_mfma_f32_16x16x32_bf16 v[22:25], v[228:231], v[216:219], v[22:25]
	v_mfma_f32_16x16x32_bf16 v[18:21], v[232:235], v[216:219], v[18:21]
	v_mfma_f32_16x16x32_bf16 v[14:17], v[236:239], v[216:219], v[14:17]
	v_mfma_f32_16x16x32_bf16 v[10:13], v[240:243], v[216:219], v[10:13]
	v_mfma_f32_16x16x32_bf16 v[6:9], v[244:247], v[216:219], v[6:9]
	v_mfma_f32_16x16x32_bf16 v[2:5], v[248:251], v[216:219], v[2:5]
	s_setprio 0
	s_cmp_lg_u32 s6, 0x40000
	s_mov_b32 s1, s6
	s_cbranch_scc1 .LBB0_235
	s_waitcnt vmcnt(1)
	v_mov_b32_e32 v98, v171
	v_mov_b32_e32 v99, v171
	s_barrier
	s_movk_i32 s1, 0xffc0
	v_and_b32_e32 v0, 15, v98
	v_ashrrev_i32_e32 v100, 1, v99
	v_lshlrev_b32_e32 v99, 1, v99
	v_lshrrev_b32_e32 v98, 2, v98
	v_and_or_b32 v0, v100, s1, v0
	v_and_b32_e32 v99, 0x80, v99
	v_and_b32_e32 v98, 12, v98
	v_or3_b32 v98, v98, v99, s0
	v_lshl_add_u32 v99, v0, 2, v197
	ds_read_b32 v106, v99
	v_add_u32_e32 v102, s5, v0
	v_mov_b64_e32 v[100:101], s[86:87]
	s_movk_i32 s6, 0xc80
	v_ashrrev_i32_e32 v99, 31, v98
	v_mad_i64_i32 v[102:103], s[0:1], v102, s6, v[100:101]
	s_waitcnt lgkmcnt(0)
	v_mul_f32_e32 v104, v158, v106
	v_mul_f32_e32 v107, v159, v106
	v_mul_f32_e32 v105, v160, v106
	v_mul_f32_e32 v108, v161, v106
	v_lshlrev_b64 v[98:99], 1, v[98:99]
	v_lshl_add_u64 v[102:103], v[102:103], 0, v[98:99]
	v_cvt_pk_bf16_f32 v105, v105, v108
	v_cvt_pk_bf16_f32 v104, v104, v107
	global_store_dwordx2 v[102:103], v[104:105], off
	v_mul_f32_e32 v104, v154, v106
	v_mul_f32_e32 v107, v155, v106
	v_mul_f32_e32 v105, v156, v106
	v_mul_f32_e32 v108, v157, v106
	v_cvt_pk_bf16_f32 v105, v105, v108
	v_cvt_pk_bf16_f32 v104, v104, v107
	global_store_dwordx2 v[102:103], v[104:105], off offset:32
	v_mul_f32_e32 v104, v150, v106
	v_mul_f32_e32 v107, v151, v106
	v_mul_f32_e32 v105, v152, v106
	v_mul_f32_e32 v108, v153, v106
	v_cvt_pk_bf16_f32 v105, v105, v108
	v_cvt_pk_bf16_f32 v104, v104, v107
	global_store_dwordx2 v[102:103], v[104:105], off offset:64
	v_mul_f32_e32 v104, v146, v106
	v_mul_f32_e32 v107, v147, v106
	v_mul_f32_e32 v105, v148, v106
	v_mul_f32_e32 v108, v149, v106
	v_cvt_pk_bf16_f32 v105, v105, v108
	v_cvt_pk_bf16_f32 v104, v104, v107
	global_store_dwordx2 v[102:103], v[104:105], off offset:96
	v_mul_f32_e32 v104, v142, v106
	v_mul_f32_e32 v107, v143, v106
	v_mul_f32_e32 v105, v144, v106
	v_mul_f32_e32 v108, v145, v106
	v_cvt_pk_bf16_f32 v105, v105, v108
	v_cvt_pk_bf16_f32 v104, v104, v107
	global_store_dwordx2 v[102:103], v[104:105], off offset:128
	v_mul_f32_e32 v104, v138, v106
	v_mul_f32_e32 v107, v139, v106
	v_mul_f32_e32 v105, v140, v106
	v_mul_f32_e32 v108, v141, v106
	v_cvt_pk_bf16_f32 v105, v105, v108
	v_cvt_pk_bf16_f32 v104, v104, v107
	global_store_dwordx2 v[102:103], v[104:105], off offset:160
	v_mul_f32_e32 v104, v134, v106
	v_mul_f32_e32 v107, v135, v106
	v_mul_f32_e32 v105, v136, v106
	v_mul_f32_e32 v108, v137, v106
	v_cvt_pk_bf16_f32 v105, v105, v108
	v_cvt_pk_bf16_f32 v104, v104, v107
	global_store_dwordx2 v[102:103], v[104:105], off offset:192
	v_mul_f32_e32 v104, v130, v106
	v_mul_f32_e32 v107, v131, v106
	v_mul_f32_e32 v105, v132, v106
	v_mul_f32_e32 v106, v133, v106
	v_cvt_pk_bf16_f32 v105, v105, v106
	v_cvt_pk_bf16_f32 v104, v104, v107
	global_store_dwordx2 v[102:103], v[104:105], off offset:224
	v_or_b32_e32 v102, 16, v0
	v_lshl_add_u32 v104, v102, 2, v197
	ds_read_b32 v104, v104
	v_add_u32_e32 v102, s5, v102
	v_mad_i64_i32 v[102:103], s[0:1], v102, s6, v[100:101]
	s_add_i32 s4, s4, 1
	s_waitcnt lgkmcnt(0)
; #define EPI_LOOP(MT_, NT_)                                                \
;   const int l_ = ltid() & 63, w_ = ltid() >> 6;                           \
;   const int wm_ = w_ >> 1, wn_ = w_ & 1, fr_ = l_ & 15, fq_ = l_ >> 4;    \
;   _Pragma("unroll") for (int mi = 0; mi < MT_; ++mi)                      \
;   _Pragma("unroll") for (int ni = 0; ni < NT_; ++ni)
; DI void qx_tile(const Params& p, int l, int rt, int ct, char* smem) {
;     ...
;   EPI_LOOP(4, 8) {
;     const int rl = wm_ * 64 + mi * 16 + fr_, col = c0 + wn_ * 128 + ni * 16 + fq_ * 4;
;     const float rs = rsv[rl];
;     uint2 o;
;     o.x = pack2(acc[mi][ni][0] * rs, acc[mi][ni][1] * rs); o.y = pack2(acc[mi][ni][2] * rs, acc[mi][ni][3] * rs);
;     *(uint2*)(QX + (size_t)(r0 + rl) * LDQ + col) = o;
;   }
;   __syncthreads();
	v_mul_f32_e32 v105, v94, v104
	v_mul_f32_e32 v106, v95, v104
	v_mul_f32_e32 v96, v96, v104
	v_mul_f32_e32 v97, v97, v104
	v_lshl_add_u64 v[94:95], v[102:103], 0, v[98:99]
	v_cvt_pk_bf16_f32 v97, v96, v97
	v_cvt_pk_bf16_f32 v96, v105, v106
	global_store_dwordx2 v[94:95], v[96:97], off
	v_mul_f32_e32 v90, v90, v104
	v_mul_f32_e32 v96, v91, v104
	v_mul_f32_e32 v91, v92, v104
	v_mul_f32_e32 v92, v93, v104
	v_cvt_pk_bf16_f32 v91, v91, v92
	v_cvt_pk_bf16_f32 v90, v90, v96
	global_store_dwordx2 v[94:95], v[90:91], off offset:32
	v_mul_f32_e32 v86, v86, v104
	v_mul_f32_e32 v90, v87, v104
	v_mul_f32_e32 v87, v88, v104
	v_mul_f32_e32 v88, v89, v104
	v_cvt_pk_bf16_f32 v87, v87, v88
	v_cvt_pk_bf16_f32 v86, v86, v90
	global_store_dwordx2 v[94:95], v[86:87], off offset:64
	v_mul_f32_e32 v82, v82, v104
	v_mul_f32_e32 v86, v83, v104
	v_mul_f32_e32 v83, v84, v104
	v_mul_f32_e32 v84, v85, v104
	v_cvt_pk_bf16_f32 v83, v83, v84
	v_cvt_pk_bf16_f32 v82, v82, v86
	global_store_dwordx2 v[94:95], v[82:83], off offset:96
	v_mul_f32_e32 v78, v78, v104
	v_mul_f32_e32 v82, v79, v104
	v_mul_f32_e32 v79, v80, v104
	v_mul_f32_e32 v80, v81, v104
	v_cvt_pk_bf16_f32 v79, v79, v80
	v_cvt_pk_bf16_f32 v78, v78, v82
	global_store_dwordx2 v[94:95], v[78:79], off offset:128
	v_mul_f32_e32 v74, v74, v104
	v_mul_f32_e32 v78, v75, v104
	v_mul_f32_e32 v75, v76, v104
	v_mul_f32_e32 v76, v77, v104
	v_cvt_pk_bf16_f32 v75, v75, v76
	v_cvt_pk_bf16_f32 v74, v74, v78
	global_store_dwordx2 v[94:95], v[74:75], off offset:160
	v_mul_f32_e32 v70, v70, v104
	v_mul_f32_e32 v74, v71, v104
	v_mul_f32_e32 v71, v72, v104
	v_mul_f32_e32 v72, v73, v104
	v_cvt_pk_bf16_f32 v71, v71, v72
	v_cvt_pk_bf16_f32 v70, v70, v74
	global_store_dwordx2 v[94:95], v[70:71], off offset:192
	v_mul_f32_e32 v66, v66, v104
	v_mul_f32_e32 v70, v67, v104
	v_mul_f32_e32 v67, v68, v104
	v_mul_f32_e32 v68, v69, v104
	v_cvt_pk_bf16_f32 v67, v67, v68
	v_cvt_pk_bf16_f32 v66, v66, v70
	global_store_dwordx2 v[94:95], v[66:67], off offset:224
	v_or_b32_e32 v66, 32, v0
	v_lshl_add_u32 v68, v66, 2, v197
	ds_read_b32 v68, v68
	v_add_u32_e32 v66, s5, v66
	v_mad_i64_i32 v[66:67], s[0:1], v66, s6, v[100:101]
	v_or_b32_e32 v0, 48, v0
	s_waitcnt lgkmcnt(0)
	v_mul_f32_e32 v69, v62, v68
	v_mul_f32_e32 v70, v63, v68
	v_mul_f32_e32 v64, v64, v68
	v_mul_f32_e32 v65, v65, v68
	v_lshl_add_u64 v[62:63], v[66:67], 0, v[98:99]
	v_cvt_pk_bf16_f32 v65, v64, v65
	v_cvt_pk_bf16_f32 v64, v69, v70
	global_store_dwordx2 v[62:63], v[64:65], off
	v_mul_f32_e32 v58, v58, v68
	v_mul_f32_e32 v64, v59, v68
	v_mul_f32_e32 v59, v60, v68
	v_mul_f32_e32 v60, v61, v68
	v_cvt_pk_bf16_f32 v59, v59, v60
	v_cvt_pk_bf16_f32 v58, v58, v64
	global_store_dwordx2 v[62:63], v[58:59], off offset:32
	v_mul_f32_e32 v54, v54, v68
	v_mul_f32_e32 v58, v55, v68
	v_mul_f32_e32 v55, v56, v68
	v_mul_f32_e32 v56, v57, v68
	v_cvt_pk_bf16_f32 v55, v55, v56
	v_cvt_pk_bf16_f32 v54, v54, v58
	global_store_dwordx2 v[62:63], v[54:55], off offset:64
	v_mul_f32_e32 v50, v50, v68
	v_mul_f32_e32 v54, v51, v68
	v_mul_f32_e32 v51, v52, v68
	v_mul_f32_e32 v52, v53, v68
	v_cvt_pk_bf16_f32 v51, v51, v52
	v_cvt_pk_bf16_f32 v50, v50, v54
	global_store_dwordx2 v[62:63], v[50:51], off offset:96
	v_mul_f32_e32 v46, v46, v68
	v_mul_f32_e32 v50, v47, v68
	v_mul_f32_e32 v47, v48, v68
	v_mul_f32_e32 v48, v49, v68
	v_cvt_pk_bf16_f32 v47, v47, v48
	v_cvt_pk_bf16_f32 v46, v46, v50
	global_store_dwordx2 v[62:63], v[46:47], off offset:128
	v_mul_f32_e32 v42, v42, v68
	v_mul_f32_e32 v46, v43, v68
	v_mul_f32_e32 v43, v44, v68
	v_mul_f32_e32 v44, v45, v68
	v_cvt_pk_bf16_f32 v43, v43, v44
	v_cvt_pk_bf16_f32 v42, v42, v46
	global_store_dwordx2 v[62:63], v[42:43], off offset:160
	v_mul_f32_e32 v38, v38, v68
	v_mul_f32_e32 v42, v39, v68
	v_mul_f32_e32 v39, v40, v68
	v_mul_f32_e32 v40, v41, v68
	v_cvt_pk_bf16_f32 v39, v39, v40
	v_cvt_pk_bf16_f32 v38, v38, v42
	global_store_dwordx2 v[62:63], v[38:39], off offset:192
	v_mul_f32_e32 v34, v34, v68
	v_mul_f32_e32 v38, v35, v68
	v_mul_f32_e32 v35, v36, v68
	v_mul_f32_e32 v36, v37, v68
	v_cvt_pk_bf16_f32 v35, v35, v36
	v_cvt_pk_bf16_f32 v34, v34, v38
	v_lshl_add_u32 v36, v0, 2, v197
	v_add_u32_e32 v0, s5, v0
	global_store_dwordx2 v[62:63], v[34:35], off offset:224
	v_mad_i64_i32 v[34:35], s[0:1], v0, s6, v[100:101]
	ds_read_b32 v0, v36
	s_mov_b64 s[0:1], 0
	s_waitcnt lgkmcnt(0)
	v_mul_f32_e32 v36, v30, v0
	v_mul_f32_e32 v37, v31, v0
	v_mul_f32_e32 v32, v32, v0
	v_mul_f32_e32 v33, v33, v0
	v_lshl_add_u64 v[30:31], v[34:35], 0, v[98:99]
	v_cvt_pk_bf16_f32 v33, v32, v33
	v_cvt_pk_bf16_f32 v32, v36, v37
	global_store_dwordx2 v[30:31], v[32:33], off
	v_mul_f32_e32 v26, v26, v0
	v_mul_f32_e32 v32, v27, v0
	v_mul_f32_e32 v27, v28, v0
	v_mul_f32_e32 v28, v29, v0
	v_cvt_pk_bf16_f32 v27, v27, v28
	v_cvt_pk_bf16_f32 v26, v26, v32
	global_store_dwordx2 v[30:31], v[26:27], off offset:32
	v_mul_f32_e32 v22, v22, v0
	v_mul_f32_e32 v26, v23, v0
	v_mul_f32_e32 v23, v24, v0
	v_mul_f32_e32 v24, v25, v0
	v_cvt_pk_bf16_f32 v23, v23, v24
	v_cvt_pk_bf16_f32 v22, v22, v26
	global_store_dwordx2 v[30:31], v[22:23], off offset:64
	v_mul_f32_e32 v18, v18, v0
	v_mul_f32_e32 v22, v19, v0
	v_mul_f32_e32 v19, v20, v0
	v_mul_f32_e32 v20, v21, v0
	v_cvt_pk_bf16_f32 v19, v19, v20
	v_cvt_pk_bf16_f32 v18, v18, v22
	global_store_dwordx2 v[30:31], v[18:19], off offset:96
	v_mul_f32_e32 v14, v14, v0
	v_mul_f32_e32 v18, v15, v0
	v_mul_f32_e32 v15, v16, v0
	v_mul_f32_e32 v16, v17, v0
	v_cvt_pk_bf16_f32 v15, v15, v16
	v_cvt_pk_bf16_f32 v14, v14, v18
	global_store_dwordx2 v[30:31], v[14:15], off offset:128
	v_mul_f32_e32 v10, v10, v0
	v_mul_f32_e32 v14, v11, v0
	v_mul_f32_e32 v11, v12, v0
	v_mul_f32_e32 v12, v13, v0
	v_cvt_pk_bf16_f32 v11, v11, v12
	v_cvt_pk_bf16_f32 v10, v10, v14
	global_store_dwordx2 v[30:31], v[10:11], off offset:160
	v_mul_f32_e32 v6, v6, v0
	v_mul_f32_e32 v10, v7, v0
	v_mul_f32_e32 v7, v8, v0
	v_mul_f32_e32 v8, v9, v0
	v_cvt_pk_bf16_f32 v7, v7, v8
	v_cvt_pk_bf16_f32 v6, v6, v10
	global_store_dwordx2 v[30:31], v[6:7], off offset:192
	v_mul_f32_e32 v2, v2, v0
	v_mul_f32_e32 v6, v3, v0
	v_mul_f32_e32 v3, v4, v0
	v_mul_f32_e32 v0, v5, v0
	v_cvt_pk_bf16_f32 v3, v3, v0
	v_cvt_pk_bf16_f32 v2, v2, v6
	global_store_dwordx2 v[30:31], v[2:3], off offset:224
	s_barrier
	s_branch .LBB0_228
